# hand-written attention unit with 8-slot LDS-DMA K/V ring (7 tiles in flight, prefetch across the two kv heads, next head's Q loads under the finalize)
# speedup vs baseline: 1.0134x; 1.0035x over previous
; #define LAS __attribute__((address_space(3)))
; __device__ __forceinline__ void attn_unit(LAS unsigned char* lds, const bf16* QKV, const bf16* KVC, bf16* O, const float* sink, int unit) {
;     const int tid = threadIdx.x, lane = tid & 63, wid = __builtin_amdgcn_readfirstlane(tid >> 6), r32 = lane & 31, hi = lane >> 5;
;     const int kvh = unit & 1, nb = (unit >> 1) & 127, b = unit >> 8;
;     const int g = wid >> 1, th = wid & 1, h = kvh * 4 + g;
;     const size_t t0 = (size_t)b * SEQ + (size_t)nb * 128;
;     bf16x8 qf[2][4];
; #pragma unroll
;     for (int qg = 0; qg < 2; ++qg)
; #pragma unroll
;         for (int ks = 0; ks < 4; ++ks) qf[qg][ks] = *(const bf16x8*)(QKV + (t0 + th * 64 + qg * 32 + r32) * NIN0 + h * 64 + ks * 16 + hi * 8);
;     LAS unsigned char* qlds = lds + 32768 + wid * 8192 + lane * 16;
; #pragma unroll
;     for (int qg = 0; qg < 2; ++qg)
; #pragma unroll
;         for (int ks = 0; ks < 4; ++ks) *(LAS bf16x8*)(qlds + (qg * 4 + ks) * 1024) = qf[qg][ks];
;     float mrun[2], lrun[2]; f32x16 o[2][2];
;     const float sk = sink[h] * LOG2E;
; #pragma unroll
;     for (int qg = 0; qg < 2; ++qg) { mrun[qg] = sk; lrun[qg] = hi ? 0.f : 1.f;
; #pragma unroll
;         for (int dg = 0; dg < 2; ++dg)
; #pragma unroll
;             for (int r = 0; r < 16; ++r) o[dg][qg][r] = 0.f; }
;     const int lkey = tid >> 3, lch = tid & 7;
;     const unsigned kw_off = (unsigned)(lkey * 128 + ((lch ^ (lkey & 7)) << 4));
;     const unsigned vw_off = (unsigned)(8192 + (lch >> 2) * 4096 + lkey * 64 + (lch & 3) * 16);
;     u32x4 kreg, vreg;
;     ...
;     LOAD_TILE(0);
.LBB0_501:
	s_cmp_lg_u32 s86, 0x100
	s_cbranch_scc1 .Latt_slow
	s_lshr_b32 s79, s8, 7
	s_and_b32 s78, s8, 0x7f
	v_readfirstlane_b32 s4, v206
	v_and_b32_e32 v204, 63, v206
	v_and_b32_e32 v205, 31, v206
	v_bfe_u32 v207, v206, 5, 1
	s_bfe_u32 s74, s4, 0x10008
	s_bfe_u32 s75, s4, 0x20006
	v_and_b32_e32 v253, 7, v205
	v_xor_b32_e32 v253, v253, v207
	v_xor_b32_e32 v254, 0, v253
	v_lshlrev_b32_e32 v254, 4, v254
	v_lshl_add_u32 v5, v205, 7, v254
	v_xor_b32_e32 v254, 2, v253
	v_lshlrev_b32_e32 v254, 4, v254
	v_lshl_add_u32 v6, v205, 7, v254
	v_xor_b32_e32 v254, 4, v253
	v_lshlrev_b32_e32 v254, 4, v254
	v_lshl_add_u32 v7, v205, 7, v254
	v_xor_b32_e32 v254, 6, v253
	v_lshlrev_b32_e32 v254, 4, v254
	v_lshl_add_u32 v136, v205, 7, v254
	v_bfe_u32 v253, v204, 2, 2
	v_lshl_add_u32 v253, v207, 2, v253
	v_lshlrev_b32_e32 v253, 6, v253
	v_bfe_u32 v254, v204, 4, 1
	v_lshl_add_u32 v253, v254, 5, v253
	v_and_b32_e32 v254, 3, v204
	v_lshl_add_u32 v137, v254, 3, v253
	v_lshlrev_b32_e32 v254, 2, v207
	v_sub_u32_e32 v203, v205, v254
	v_lshrrev_b32_e32 v253, 3, v206
	v_and_b32_e32 v254, 7, v206
	v_and_b32_e32 v255, 7, v253
	v_xor_b32_e32 v255, v255, v254
	v_lshlrev_b32_e32 v255, 4, v255
	v_mul_u32_u24_e32 v204, 0xe00, v253
	v_add_u32_e32 v160, v204, v255
	v_lshl_add_u32 v162, v253, 9, v255
	v_bfe_u32 v253, v206, 2, 6
	v_lshrrev_b32_e32 v254, 8, v206
	v_and_b32_e32 v255, 3, v206
	v_lshl_add_u32 v254, v254, 2, v255
	v_lshlrev_b32_e32 v254, 4, v254
	v_add_u32_e32 v254, 0x100, v254
	v_mul_u32_u24_e32 v204, 0xe00, v253
	v_add_u32_e32 v161, v204, v254
	v_lshl_add_u32 v163, v253, 9, v254
	s_lshr_b32 s100, s4, 6
	s_lshl_b32 s100, s100, 10
	s_mov_b32 s76, 0
	s_mov_b32 s91, 0
	s_and_b32 s4, s91, 7
	s_lshl_b32 s4, s4, 14
	s_add_u32 s4, s4, s100
	s_min_u32 s91, s91, 19
	s_cmp_ge_u32 s91, 10
	s_cselect_b32 s88, 1, 0
	s_mul_i32 s12, s88, 10
	s_sub_u32 s91, s91, s12
	s_lshl_b32 s88, s88, 7
	s_mov_b32 m0, s4
	s_cmp_lt_u32 s91, 6
	s_cbranch_scc0 .Latt_ldc_pro0
	s_lshl_b32 s5, s78, 7
	s_lshl_b32 s12, s91, 6
	s_add_u32 s12, s12, s5
	s_sub_u32 s12, s12, 0x80
	s_cmp_lt_u32 s12, 0x4000
	s_cselect_b32 s12, s12, s5
	s_lshl_b32 s5, s79, 14
	s_add_u32 s12, s12, s5
	s_mul_i32 s12, s12, 0xe00
	s_add_u32 s12, s12, s88
	s_add_u32 s12, s12, 0x400
	s_add_u32 s82, s48, s12
	s_addc_u32 s83, s49, 0
	global_load_lds_dwordx4 v160, s[82:83]
	s_add_u32 m0, s4, 0x2000
	s_nop 0
	global_load_lds_dwordx4 v161, s[82:83]
	s_branch .Latt_ldd_pro0
.Latt_ldc_pro0:
	s_sub_u32 s5, s91, 6
	s_lshl_b32 s5, s5, 6
	s_lshl_b32 s12, s79, 8
	s_add_u32 s5, s5, s12
	s_lshl_b32 s5, s5, 9
	s_add_u32 s5, s5, s88
	s_add_u32 s5, s5, 0x3200000
	s_add_u32 s82, s50, s5
	s_addc_u32 s83, s51, 0
	global_load_lds_dwordx4 v162, s[82:83]
	s_add_u32 m0, s4, 0x2000
	s_nop 0
	global_load_lds_dwordx4 v163, s[82:83]
.Latt_ldd_pro0:
	v_readlane_b32 s40, v252, 13
	v_readlane_b32 s41, v252, 14
	s_lshl_b32 s4, s8, 7
	s_lshl_b32 s5, s74, 6
	s_add_u32 s4, s4, s5
	s_lshl_b32 s12, s76, 2
	s_add_u32 s12, s12, s75
	s_lshl_b32 s88, s12, 7
	s_mul_i32 s5, s4, 0xe00
	s_add_u32 s5, s5, s88
	s_add_u32 s52, s48, s5
	s_addc_u32 s53, s49, 0
	v_and_b32_e32 v205, 31, v206
	v_bfe_u32 v207, v206, 5, 1
	v_mul_u32_u24_e32 v204, 0xe00, v205
	v_lshl_add_u32 v204, v207, 4, v204
	v_add_u32_e32 v253, 0x1c000, v204
	global_load_dwordx4 v[208:211], v204, s[52:53] offset:0
	global_load_dwordx4 v[212:215], v204, s[52:53] offset:32
	global_load_dwordx4 v[216:219], v204, s[52:53] offset:64
	global_load_dwordx4 v[220:223], v204, s[52:53] offset:96
	global_load_dwordx4 v[224:227], v253, s[52:53] offset:0
	global_load_dwordx4 v[228:231], v253, s[52:53] offset:32
	global_load_dwordx4 v[232:235], v253, s[52:53] offset:64
	global_load_dwordx4 v[236:239], v253, s[52:53] offset:96
	s_lshl_b32 s12, s12, 2
	s_load_dword s47, s[40:41], s12
	s_mov_b32 s91, 1
	s_and_b32 s4, s91, 7
	s_lshl_b32 s4, s4, 14
	s_add_u32 s4, s4, s100
	s_min_u32 s91, s91, 19
	s_cmp_ge_u32 s91, 10
	s_cselect_b32 s88, 1, 0
	s_mul_i32 s12, s88, 10
	s_sub_u32 s91, s91, s12
	s_lshl_b32 s88, s88, 7
	s_mov_b32 m0, s4
	s_cmp_lt_u32 s91, 6
	s_cbranch_scc0 .Latt_ldc_pro1
	s_lshl_b32 s5, s78, 7
	s_lshl_b32 s12, s91, 6
	s_add_u32 s12, s12, s5
	s_sub_u32 s12, s12, 0x80
	s_cmp_lt_u32 s12, 0x4000
	s_cselect_b32 s12, s12, s5
	s_lshl_b32 s5, s79, 14
	s_add_u32 s12, s12, s5
	s_mul_i32 s12, s12, 0xe00
	s_add_u32 s12, s12, s88
	s_add_u32 s12, s12, 0x400
	s_add_u32 s82, s48, s12
	s_addc_u32 s83, s49, 0
	global_load_lds_dwordx4 v160, s[82:83]
	s_add_u32 m0, s4, 0x2000
	s_nop 0
	global_load_lds_dwordx4 v161, s[82:83]
	s_branch .Latt_ldd_pro1

.Latt_ldd_pro1:
	s_mov_b32 s91, 2
	s_and_b32 s4, s91, 7
	s_lshl_b32 s4, s4, 14
	s_add_u32 s4, s4, s100
	s_min_u32 s91, s91, 19
	s_cmp_ge_u32 s91, 10
	s_cselect_b32 s88, 1, 0
	s_mul_i32 s12, s88, 10
	s_sub_u32 s91, s91, s12
	s_lshl_b32 s88, s88, 7
	s_mov_b32 m0, s4
	s_cmp_lt_u32 s91, 6
	s_cbranch_scc0 .Latt_ldc_pro2
	s_lshl_b32 s5, s78, 7
	s_lshl_b32 s12, s91, 6
	s_add_u32 s12, s12, s5
	s_sub_u32 s12, s12, 0x80
	s_cmp_lt_u32 s12, 0x4000
	s_cselect_b32 s12, s12, s5
	s_lshl_b32 s5, s79, 14
	s_add_u32 s12, s12, s5
	s_mul_i32 s12, s12, 0xe00
	s_add_u32 s12, s12, s88
	s_add_u32 s12, s12, 0x400
	s_add_u32 s82, s48, s12
	s_addc_u32 s83, s49, 0
	global_load_lds_dwordx4 v160, s[82:83]
	s_add_u32 m0, s4, 0x2000
	s_nop 0
	global_load_lds_dwordx4 v161, s[82:83]
	s_branch .Latt_ldd_pro2

.Latt_ldd_pro2:
	s_mov_b32 s91, 3
	s_and_b32 s4, s91, 7
	s_lshl_b32 s4, s4, 14
	s_add_u32 s4, s4, s100
	s_min_u32 s91, s91, 19
	s_cmp_ge_u32 s91, 10
	s_cselect_b32 s88, 1, 0
	s_mul_i32 s12, s88, 10
	s_sub_u32 s91, s91, s12
	s_lshl_b32 s88, s88, 7
	s_mov_b32 m0, s4
	s_cmp_lt_u32 s91, 6
	s_cbranch_scc0 .Latt_ldc_pro3
	s_lshl_b32 s5, s78, 7
	s_lshl_b32 s12, s91, 6
	s_add_u32 s12, s12, s5
	s_sub_u32 s12, s12, 0x80
	s_cmp_lt_u32 s12, 0x4000
	s_cselect_b32 s12, s12, s5
	s_lshl_b32 s5, s79, 14
	s_add_u32 s12, s12, s5
	s_mul_i32 s12, s12, 0xe00
	s_add_u32 s12, s12, s88
	s_add_u32 s12, s12, 0x400
	s_add_u32 s82, s48, s12
	s_addc_u32 s83, s49, 0
	global_load_lds_dwordx4 v160, s[82:83]
	s_add_u32 m0, s4, 0x2000
	s_nop 0
	global_load_lds_dwordx4 v161, s[82:83]
	s_branch .Latt_ldd_pro3

.Latt_ldd_pro3:
	s_mov_b32 s91, 4
	s_and_b32 s4, s91, 7
	s_lshl_b32 s4, s4, 14
	s_add_u32 s4, s4, s100
	s_min_u32 s91, s91, 19
	s_cmp_ge_u32 s91, 10
	s_cselect_b32 s88, 1, 0
	s_mul_i32 s12, s88, 10
	s_sub_u32 s91, s91, s12
	s_lshl_b32 s88, s88, 7
	s_mov_b32 m0, s4
	s_cmp_lt_u32 s91, 6
	s_cbranch_scc0 .Latt_ldc_pro4
	s_lshl_b32 s5, s78, 7
	s_lshl_b32 s12, s91, 6
	s_add_u32 s12, s12, s5
	s_sub_u32 s12, s12, 0x80
	s_cmp_lt_u32 s12, 0x4000
	s_cselect_b32 s12, s12, s5
	s_lshl_b32 s5, s79, 14
	s_add_u32 s12, s12, s5
	s_mul_i32 s12, s12, 0xe00
	s_add_u32 s12, s12, s88
	s_add_u32 s12, s12, 0x400
	s_add_u32 s82, s48, s12
	s_addc_u32 s83, s49, 0
	global_load_lds_dwordx4 v160, s[82:83]
	s_add_u32 m0, s4, 0x2000
	s_nop 0
	global_load_lds_dwordx4 v161, s[82:83]
	s_branch .Latt_ldd_pro4

.Latt_ldd_pro4:
	s_mov_b32 s91, 5
	s_and_b32 s4, s91, 7
	s_lshl_b32 s4, s4, 14
	s_add_u32 s4, s4, s100
	s_min_u32 s91, s91, 19
	s_cmp_ge_u32 s91, 10
	s_cselect_b32 s88, 1, 0
	s_mul_i32 s12, s88, 10
	s_sub_u32 s91, s91, s12
	s_lshl_b32 s88, s88, 7
	s_mov_b32 m0, s4
	s_cmp_lt_u32 s91, 6
	s_cbranch_scc0 .Latt_ldc_pro5
	s_lshl_b32 s5, s78, 7
	s_lshl_b32 s12, s91, 6
	s_add_u32 s12, s12, s5
	s_sub_u32 s12, s12, 0x80
	s_cmp_lt_u32 s12, 0x4000
	s_cselect_b32 s12, s12, s5
	s_lshl_b32 s5, s79, 14
	s_add_u32 s12, s12, s5
	s_mul_i32 s12, s12, 0xe00
	s_add_u32 s12, s12, s88
	s_add_u32 s12, s12, 0x400
	s_add_u32 s82, s48, s12
	s_addc_u32 s83, s49, 0
	global_load_lds_dwordx4 v160, s[82:83]
	s_add_u32 m0, s4, 0x2000
	s_nop 0
	global_load_lds_dwordx4 v161, s[82:83]
	s_branch .Latt_ldd_pro5

.Latt_ldd_pro5:
	s_mov_b32 s91, 6
	s_and_b32 s4, s91, 7
	s_lshl_b32 s4, s4, 14
	s_add_u32 s4, s4, s100
	s_min_u32 s91, s91, 19
	s_cmp_ge_u32 s91, 10
	s_cselect_b32 s88, 1, 0
	s_mul_i32 s12, s88, 10
	s_sub_u32 s91, s91, s12
	s_lshl_b32 s88, s88, 7
	s_mov_b32 m0, s4
	s_cmp_lt_u32 s91, 6
	s_cbranch_scc0 .Latt_ldc_pro6
	s_lshl_b32 s5, s78, 7
	s_lshl_b32 s12, s91, 6
	s_add_u32 s12, s12, s5
	s_sub_u32 s12, s12, 0x80
	s_cmp_lt_u32 s12, 0x4000
	s_cselect_b32 s12, s12, s5
	s_lshl_b32 s5, s79, 14
	s_add_u32 s12, s12, s5
	s_mul_i32 s12, s12, 0xe00
	s_add_u32 s12, s12, s88
	s_add_u32 s12, s12, 0x400
	s_add_u32 s82, s48, s12
	s_addc_u32 s83, s49, 0
	global_load_lds_dwordx4 v160, s[82:83]
	s_add_u32 m0, s4, 0x2000
	s_nop 0
	global_load_lds_dwordx4 v161, s[82:83]
	s_branch .Latt_ldd_pro6

; #define LAS __attribute__((address_space(3)))
; __device__ __forceinline__ void attn_unit(LAS unsigned char* lds, const bf16* QKV, const bf16* KVC, bf16* O, const float* sink, int unit) {
;     ...
;     float mrun[2], lrun[2]; f32x16 o[2][2];
;     const float sk = sink[h] * LOG2E;
; #pragma unroll
;     for (int qg = 0; qg < 2; ++qg) { mrun[qg] = sk; lrun[qg] = hi ? 0.f : 1.f;
; #pragma unroll
;         for (int dg = 0; dg < 2; ++dg)
; #pragma unroll
;             for (int r = 0; r < 16; ++r) o[dg][qg][r] = 0.f; }
;     ...
;     for (int tl = 0; tl < 10; ++tl) {
;         LAS unsigned char* buf = lds + (tl & 1) * 16384;
;         *(LAS u32x4*)(buf + kw_off) = kreg; *(LAS u32x4*)(buf + vw_off) = vreg;
;         if (tl + 1 < 10) LOAD_TILE(tl + 1);
;         __syncthreads();
.Latt_ldd_pro6:
.Latt_unit:
	s_lshl_b32 s4, s8, 7
	s_lshl_b32 s5, s74, 6
	s_add_u32 s4, s4, s5
	s_lshl_b32 s12, s76, 2
	s_add_u32 s12, s12, s75
	s_lshl_b32 s88, s12, 7
	s_lshl_b32 s4, s4, 11
	s_add_u32 s4, s4, s88
	s_add_u32 s4, s4, 0x12800000
	s_add_u32 s98, s50, s4
	s_addc_u32 s99, s51, 0
	v_mov_b32_e32 v8, 0
	v_mov_b32_e32 v9, 0
	v_mov_b32_e32 v10, 0
	v_mov_b32_e32 v11, 0
	v_mov_b32_e32 v12, 0
	v_mov_b32_e32 v13, 0
	v_mov_b32_e32 v14, 0
	v_mov_b32_e32 v15, 0
	v_mov_b32_e32 v16, 0
	v_mov_b32_e32 v17, 0
	v_mov_b32_e32 v18, 0
	v_mov_b32_e32 v19, 0
	v_mov_b32_e32 v20, 0
	v_mov_b32_e32 v21, 0
	v_mov_b32_e32 v22, 0
	v_mov_b32_e32 v23, 0
	v_mov_b32_e32 v24, 0
	v_mov_b32_e32 v25, 0
	v_mov_b32_e32 v26, 0
	v_mov_b32_e32 v27, 0
	v_mov_b32_e32 v28, 0
	v_mov_b32_e32 v29, 0
	v_mov_b32_e32 v30, 0
	v_mov_b32_e32 v31, 0
	v_mov_b32_e32 v32, 0
	v_mov_b32_e32 v33, 0
	v_mov_b32_e32 v34, 0
	v_mov_b32_e32 v35, 0
	v_mov_b32_e32 v36, 0
	v_mov_b32_e32 v37, 0
	v_mov_b32_e32 v38, 0
	v_mov_b32_e32 v39, 0
	v_mov_b32_e32 v40, 0
	v_mov_b32_e32 v41, 0
	v_mov_b32_e32 v42, 0
	v_mov_b32_e32 v43, 0
	v_mov_b32_e32 v44, 0
	v_mov_b32_e32 v45, 0
	v_mov_b32_e32 v46, 0
	v_mov_b32_e32 v47, 0
	v_mov_b32_e32 v48, 0
	v_mov_b32_e32 v49, 0
	v_mov_b32_e32 v50, 0
	v_mov_b32_e32 v51, 0
	v_mov_b32_e32 v52, 0
	v_mov_b32_e32 v53, 0
	v_mov_b32_e32 v54, 0
	v_mov_b32_e32 v55, 0
	v_mov_b32_e32 v56, 0
	v_mov_b32_e32 v57, 0
	v_mov_b32_e32 v58, 0
	v_mov_b32_e32 v59, 0
	v_mov_b32_e32 v60, 0
	v_mov_b32_e32 v61, 0
	v_mov_b32_e32 v62, 0
	v_mov_b32_e32 v63, 0
	v_mov_b32_e32 v64, 0
	v_mov_b32_e32 v65, 0
	v_mov_b32_e32 v66, 0
	v_mov_b32_e32 v67, 0
	v_mov_b32_e32 v68, 0
	v_mov_b32_e32 v69, 0
	v_mov_b32_e32 v70, 0
	v_mov_b32_e32 v71, 0
	v_bfe_u32 v207, v206, 5, 1
	v_cmp_eq_u32_e32 vcc, 0, v207
	s_waitcnt lgkmcnt(0)
	v_mov_b32_e32 v254, s47
	v_mul_f32_e32 v1, 0x3fb8aa3b, v254
	v_mov_b32_e32 v2, v1
	v_cndmask_b32_e64 v3, 0, 1.0, vcc
	v_mov_b32_e32 v4, v3
	s_mov_b32 s77, 0
.Latt_tile:
	s_waitcnt vmcnt(12)
	s_barrier
	s_mul_i32 s91, s76, 10
	s_add_u32 s91, s91, s77
	s_and_b32 s101, s91, 7
	s_lshl_b32 s101, s101, 14
	s_add_u32 s91, s91, 7
	s_and_b32 s4, s91, 7
	s_lshl_b32 s4, s4, 14
	s_add_u32 s4, s4, s100
	s_min_u32 s91, s91, 19
	s_cmp_ge_u32 s91, 10
	s_cselect_b32 s88, 1, 0
	s_mul_i32 s12, s88, 10
	s_sub_u32 s91, s91, s12
	s_lshl_b32 s88, s88, 7
	s_mov_b32 m0, s4
	s_cmp_lt_u32 s91, 6
	s_cbranch_scc0 .Latt_ldc_loop
	s_lshl_b32 s5, s78, 7
	s_lshl_b32 s12, s91, 6
	s_add_u32 s12, s12, s5
	s_sub_u32 s12, s12, 0x80
	s_cmp_lt_u32 s12, 0x4000
	s_cselect_b32 s12, s12, s5
	s_lshl_b32 s5, s79, 14
	s_add_u32 s12, s12, s5
	s_mul_i32 s12, s12, 0xe00
	s_add_u32 s12, s12, s88
	s_add_u32 s12, s12, 0x400
	s_add_u32 s82, s48, s12
	s_addc_u32 s83, s49, 0
	global_load_lds_dwordx4 v160, s[82:83]
	s_add_u32 m0, s4, 0x2000
	s_nop 0
	global_load_lds_dwordx4 v161, s[82:83]
	s_branch .Latt_ldd_loop

; #define LAS __attribute__((address_space(3)))
; __device__ __forceinline__ int crow(int r, int hi) { return (r & 3) + 8 * (r >> 2) + 4 * hi; }
; __device__ __forceinline__ void attn_unit(LAS unsigned char* lds, const bf16* QKV, const bf16* KVC, bf16* O, const float* sink, int unit) {
;     ...
;     for (int tl = 0; tl < 10; ++tl) {
;         LAS unsigned char* buf = lds + (tl & 1) * 16384;
;         *(LAS u32x4*)(buf + kw_off) = kreg; *(LAS u32x4*)(buf + vw_off) = vreg;
;         if (tl + 1 < 10) LOAD_TILE(tl + 1);
;         __syncthreads();
;         int cls = 1;
;         if (tl < 6) { const int kpos0 = (nb - 1) * 128 + tl * 64;
;             if (kpos0 < 0 || kpos0 >= SEQ || tl < th || tl > th + 4) cls = 0; else cls = (tl == th || tl == th + 4) ? 2 : 1; }
;         if (cls != 0) {
;         f32x16 sacc[2][2];
; #pragma unroll
;         for (int kg = 0; kg < 2; ++kg)
; #pragma unroll
;             for (int qg = 0; qg < 2; ++qg)
; #pragma unroll
;                 for (int r = 0; r < 16; ++r) sacc[kg][qg][r] = -mrun[qg];
; #pragma unroll
;         for (int kg = 0; kg < 2; ++kg)
; #pragma unroll
;             for (int ks = 0; ks < 4; ++ks) {
;                 const bf16x8 kf = *(const LAS bf16x8*)(buf + kr_base + kg * 4096 + ((((ks * 2 + hi) ^ (r32 & 7))) << 4));
; #pragma unroll
;                 for (int qg = 0; qg < 2; ++qg) { const bf16x8 qv = *(const LAS bf16x8*)(qlds + (qg * 4 + ks) * 1024);
;                     sacc[kg][qg] = __builtin_amdgcn_mfma_f32_32x32x16_bf16(kf, qv, sacc[kg][qg], 0, 0, 0); }
;             }
;         bf16x8 pf[2][2][2];
; #pragma unroll
;         for (int qg = 0; qg < 2; ++qg) {
;             if (cls == 2) {
;                 const int qi = th * 64 + qg * 32 + r32;
; #pragma unroll
;                 for (int kg = 0; kg < 2; ++kg)
; #pragma unroll
;                     for (int r = 0; r < 16; ++r) { const int kj = tl * 64 + kg * 32 + crow(r, hi);
;                         const bool valid = (kj >= qi) && (kj <= qi + 256); sacc[kg][qg][r] = valid ? sacc[kg][qg][r] : -1.0e30f; }
;             }
.Latt_ldd_loop:
	v_add_u32_e32 v164, s101, v5
	v_add_u32_e32 v165, s101, v6
	v_add_u32_e32 v166, s101, v7
	v_add_u32_e32 v167, s101, v136
	v_add_u32_e32 v199, s101, v137
	s_mov_b32 s80, 1
	s_cmp_lt_u32 s77, 6
	s_cbranch_scc0 .Latt_cd_loop
	s_lshl_b32 s5, s78, 7
	s_sub_u32 s5, s5, 0x80
	s_lshl_b32 s12, s77, 6
	s_add_u32 s5, s5, s12
	s_add_u32 s12, s74, 4
	s_cmp_lt_u32 s5, 0x4000
	s_cselect_b32 s80, 1, 0
	s_cmp_lt_u32 s77, s74
	s_cselect_b32 s80, 0, s80
	s_cmp_gt_u32 s77, s12
	s_cselect_b32 s80, 0, s80
	s_cmp_eq_u32 s77, s74
	s_cselect_b32 s88, 2, 1
	s_cmp_eq_u32 s77, s12
	s_cselect_b32 s88, 3, s88
	s_cmp_eq_u32 s80, 0
	s_cselect_b32 s80, 0, s88
.Latt_cd_loop:
	s_cmp_eq_u32 s80, 0
	s_cbranch_scc1 .Latt_skip
	ds_read_b128 v[240:243], v164 offset:0
	ds_read_b128 v[244:247], v164 offset:4096
	ds_read_b128 v[248:251], v165 offset:0
	s_waitcnt lgkmcnt(2)
	v_mfma_f32_32x32x16_bf16 v[72:87], v[240:243], v[208:211], 0
	ds_read_b128 v[240:243], v165 offset:4096
	s_waitcnt lgkmcnt(2)
	v_mfma_f32_32x32x16_bf16 v[104:119], v[244:247], v[208:211], 0
	ds_read_b128 v[244:247], v166 offset:0
	s_waitcnt lgkmcnt(2)
	v_mfma_f32_32x32x16_bf16 v[72:87], v[248:251], v[212:215], v[72:87]
	ds_read_b128 v[248:251], v166 offset:4096
	s_waitcnt lgkmcnt(2)
	v_mfma_f32_32x32x16_bf16 v[104:119], v[240:243], v[212:215], v[104:119]
	ds_read_b128 v[240:243], v167 offset:0
	s_waitcnt lgkmcnt(2)
	v_mfma_f32_32x32x16_bf16 v[72:87], v[244:247], v[216:219], v[72:87]
	ds_read_b128 v[244:247], v167 offset:4096
	s_waitcnt lgkmcnt(2)
	v_mfma_f32_32x32x16_bf16 v[104:119], v[248:251], v[216:219], v[104:119]
	ds_read_b128 v[248:251], v164 offset:0
	s_waitcnt lgkmcnt(2)
	v_mfma_f32_32x32x16_bf16 v[72:87], v[240:243], v[220:223], v[72:87]
	ds_read_b128 v[240:243], v164 offset:4096
	s_waitcnt lgkmcnt(2)
	v_mfma_f32_32x32x16_bf16 v[104:119], v[244:247], v[220:223], v[104:119]
	ds_read_b128 v[244:247], v165 offset:0
	s_nop 11
	s_cmp_lt_u32 s80, 2
	s_cbranch_scc1 .Latt_mk_done_p0q0
	v_mov_b32_e32 v253, 0xf149f2ca
	s_cmp_eq_u32 s80, 3
	s_cbranch_scc1 .Latt_mk_up_p0q0
	v_cmp_ge_i32_e64 s[40:41], 0, v203
	v_cmp_ge_i32_e64 s[46:47], 1, v203
	v_cmp_ge_i32_e64 s[52:53], 2, v203
	v_cmp_ge_i32_e64 s[54:55], 3, v203
	v_cndmask_b32_e64 v72, v253, v72, s[40:41]
	v_cmp_ge_i32_e64 s[40:41], 8, v203
	v_cndmask_b32_e64 v73, v253, v73, s[46:47]
	v_cmp_ge_i32_e64 s[46:47], 9, v203
	v_cndmask_b32_e64 v74, v253, v74, s[52:53]
	v_cmp_ge_i32_e64 s[52:53], 10, v203
	v_cndmask_b32_e64 v75, v253, v75, s[54:55]
	v_cmp_ge_i32_e64 s[54:55], 11, v203
	v_cndmask_b32_e64 v76, v253, v76, s[40:41]
	v_cmp_ge_i32_e64 s[40:41], 16, v203
	v_cndmask_b32_e64 v77, v253, v77, s[46:47]
	v_cmp_ge_i32_e64 s[46:47], 17, v203
	v_cndmask_b32_e64 v78, v253, v78, s[52:53]
	v_cmp_ge_i32_e64 s[52:53], 18, v203
	v_cndmask_b32_e64 v79, v253, v79, s[54:55]
	v_cmp_ge_i32_e64 s[54:55], 19, v203
	v_cndmask_b32_e64 v80, v253, v80, s[40:41]
	v_cmp_ge_i32_e64 s[40:41], 24, v203
	v_cndmask_b32_e64 v81, v253, v81, s[46:47]
	v_cmp_ge_i32_e64 s[46:47], 25, v203
	v_cndmask_b32_e64 v82, v253, v82, s[52:53]
	v_cmp_ge_i32_e64 s[52:53], 26, v203
	v_cndmask_b32_e64 v83, v253, v83, s[54:55]
	v_cmp_ge_i32_e64 s[54:55], 27, v203
	v_cndmask_b32_e64 v84, v253, v84, s[40:41]
	v_cndmask_b32_e64 v85, v253, v85, s[46:47]
	v_cndmask_b32_e64 v86, v253, v86, s[52:53]
	v_cndmask_b32_e64 v87, v253, v87, s[54:55]
	s_branch .Latt_mk_done_p0q0
.Latt_mk_up_p0q0:
	v_cmp_le_i32_e64 s[40:41], 0, v203
	v_cmp_le_i32_e64 s[46:47], 1, v203
	v_cmp_le_i32_e64 s[52:53], 2, v203
	v_cmp_le_i32_e64 s[54:55], 3, v203
	v_cndmask_b32_e64 v72, v253, v72, s[40:41]
	v_cmp_le_i32_e64 s[40:41], 8, v203
	v_cndmask_b32_e64 v73, v253, v73, s[46:47]
	v_cmp_le_i32_e64 s[46:47], 9, v203
	v_cndmask_b32_e64 v74, v253, v74, s[52:53]
	v_cmp_le_i32_e64 s[52:53], 10, v203
	v_cndmask_b32_e64 v75, v253, v75, s[54:55]
	v_cmp_le_i32_e64 s[54:55], 11, v203
	v_cndmask_b32_e64 v76, v253, v76, s[40:41]
	v_cmp_le_i32_e64 s[40:41], 16, v203
	v_cndmask_b32_e64 v77, v253, v77, s[46:47]
	v_cmp_le_i32_e64 s[46:47], 17, v203
	v_cndmask_b32_e64 v78, v253, v78, s[52:53]
	v_cmp_le_i32_e64 s[52:53], 18, v203
	v_cndmask_b32_e64 v79, v253, v79, s[54:55]
	v_cmp_le_i32_e64 s[54:55], 19, v203
	v_cndmask_b32_e64 v80, v253, v80, s[40:41]
	v_cmp_le_i32_e64 s[40:41], 24, v203
	v_cndmask_b32_e64 v81, v253, v81, s[46:47]
	v_cmp_le_i32_e64 s[46:47], 25, v203
	v_cndmask_b32_e64 v82, v253, v82, s[52:53]
	v_cmp_le_i32_e64 s[52:53], 26, v203
	v_cndmask_b32_e64 v83, v253, v83, s[54:55]
	v_cmp_le_i32_e64 s[54:55], 27, v203
	v_cndmask_b32_e64 v84, v253, v84, s[40:41]
	v_cndmask_b32_e64 v85, v253, v85, s[46:47]
	v_cndmask_b32_e64 v86, v253, v86, s[52:53]
	v_cndmask_b32_e64 v87, v253, v87, s[54:55]
	v_mov_b32_e32 v104, v253
	v_mov_b32_e32 v105, v253
	v_mov_b32_e32 v106, v253
	v_mov_b32_e32 v107, v253
	v_mov_b32_e32 v108, v253
	v_mov_b32_e32 v109, v253
	v_mov_b32_e32 v110, v253
	v_mov_b32_e32 v111, v253
	v_mov_b32_e32 v112, v253
	v_mov_b32_e32 v113, v253
	v_mov_b32_e32 v114, v253
	v_mov_b32_e32 v115, v253
	v_mov_b32_e32 v116, v253
	v_mov_b32_e32 v117, v253
	v_mov_b32_e32 v118, v253
	v_mov_b32_e32 v119, v253
; __device__ __forceinline__ unsigned cvt_pk_bf16(float lo, float hi) { f32x2_t v = {lo, hi}; bf16x2_t b = __builtin_convertvector(v, bf16x2_t); return __builtin_bit_cast(unsigned, b); }
; __device__ __forceinline__ void attn_unit(LAS unsigned char* lds, const bf16* QKV, const bf16* KVC, bf16* O, const float* sink, int unit) {
;     ...
;             float mxa = fmaxf(sacc[0][qg][0], sacc[1][qg][0]), mxb = fmaxf(sacc[0][qg][1], sacc[1][qg][1]);
; #pragma unroll
;             for (int r = 2; r < 16; r += 2) { mxa = fmaxf(fmaxf(mxa, sacc[0][qg][r]), sacc[1][qg][r]); mxb = fmaxf(fmaxf(mxb, sacc[0][qg][r + 1]), sacc[1][qg][r + 1]); }
;             float mx = fmaxf(mxa, mxb);
;             mx = fmaxf(mx, __shfl_xor(mx, 32));
;             if (__any(mx > 0.f)) {
;                 const float dl = fmaxf(mx, 0.f); mrun[qg] += dl;
;                 const float alpha = __builtin_amdgcn_exp2f(-dl); lrun[qg] *= alpha;
; #pragma unroll
;                 for (int kg = 0; kg < 2; ++kg)
; #pragma unroll
;                     for (int r = 0; r < 16; ++r) sacc[kg][qg][r] -= dl;
; #pragma unroll
;                 for (int dg = 0; dg < 2; ++dg)
; #pragma unroll
;                     for (int r = 0; r < 16; ++r) o[dg][qg][r] *= alpha;
;             }
;             float psa = 0.f, psb = 0.f;
; #pragma unroll
;             for (int kg = 0; kg < 2; ++kg)
; #pragma unroll
;                 for (int r = 0; r < 16; r += 2) { const float p0 = __builtin_amdgcn_exp2f(sacc[kg][qg][r]), p1 = __builtin_amdgcn_exp2f(sacc[kg][qg][r + 1]); sacc[kg][qg][r] = p0; sacc[kg][qg][r + 1] = p1; psa += p0; psb += p1; }
;             lrun[qg] += psa + psb;
; #pragma unroll
;             for (int kg = 0; kg < 2; ++kg)
; #pragma unroll
;                 for (int s = 0; s < 2; ++s) { u32x4 w;
;                     w.x = cvt_pk_bf16(sacc[kg][qg][8 * s + 0], sacc[kg][qg][8 * s + 1]); w.y = cvt_pk_bf16(sacc[kg][qg][8 * s + 2], sacc[kg][qg][8 * s + 3]);
;                     w.z = cvt_pk_bf16(sacc[kg][qg][8 * s + 4], sacc[kg][qg][8 * s + 5]); w.w = cvt_pk_bf16(sacc[kg][qg][8 * s + 6], sacc[kg][qg][8 * s + 7]);
;                     pf[kg][qg][s] = __builtin_bit_cast(bf16x8, w); }
.Latt_mk_done_p0q0:
	s_waitcnt lgkmcnt(2)
	v_mfma_f32_32x32x16_bf16 v[88:103], v[248:251], v[224:227], 0
	ds_read_b128 v[248:251], v165 offset:4096
	v_max3_f32 v204, v72, v73, v74
	v_max3_f32 v205, v104, v105, v106
	v_max3_f32 v204, v204, v75, v76
	v_max3_f32 v205, v205, v107, v108
	v_max3_f32 v204, v204, v77, v78
	v_max3_f32 v205, v205, v109, v110
	v_max3_f32 v204, v204, v79, v80
	v_max3_f32 v205, v205, v111, v112
	v_max3_f32 v204, v204, v81, v82
	v_max3_f32 v205, v205, v113, v114
	v_max3_f32 v204, v204, v83, v84
	v_max3_f32 v205, v205, v115, v116
	s_waitcnt lgkmcnt(2)
	v_mfma_f32_32x32x16_bf16 v[120:135], v[240:243], v[224:227], 0
	ds_read_b128 v[240:243], v166 offset:0
	v_max3_f32 v204, v204, v85, v86
	v_max3_f32 v205, v205, v117, v118
	v_max3_f32 v204, v204, v87, v119
	v_max_f32_e32 v204, v204, v205
	v_mov_b32_e32 v205, v204
	s_nop 1
	v_permlane32_swap_b32_e32 v204, v205
	v_max_f32_e32 v204, v204, v205
	v_max_f32_e32 v204, v204, v1
	v_cmp_gt_f32_e32 vcc, v204, v1
	s_cbranch_vccz .Latt_nr_p0q0
	v_sub_f32_e32 v254, v1, v204
	v_exp_f32_e32 v254, v254
	s_nop 0
	v_mul_f32_e32 v3, v3, v254
	v_pk_mul_f32 v[8:9], v[8:9], v[254:255] op_sel_hi:[1,0]
	v_pk_mul_f32 v[10:11], v[10:11], v[254:255] op_sel_hi:[1,0]
	v_pk_mul_f32 v[12:13], v[12:13], v[254:255] op_sel_hi:[1,0]
	v_pk_mul_f32 v[14:15], v[14:15], v[254:255] op_sel_hi:[1,0]
	v_pk_mul_f32 v[16:17], v[16:17], v[254:255] op_sel_hi:[1,0]
	v_pk_mul_f32 v[18:19], v[18:19], v[254:255] op_sel_hi:[1,0]
	v_pk_mul_f32 v[20:21], v[20:21], v[254:255] op_sel_hi:[1,0]
	v_pk_mul_f32 v[22:23], v[22:23], v[254:255] op_sel_hi:[1,0]
	v_pk_mul_f32 v[40:41], v[40:41], v[254:255] op_sel_hi:[1,0]
	v_pk_mul_f32 v[42:43], v[42:43], v[254:255] op_sel_hi:[1,0]
	v_pk_mul_f32 v[44:45], v[44:45], v[254:255] op_sel_hi:[1,0]
	v_pk_mul_f32 v[46:47], v[46:47], v[254:255] op_sel_hi:[1,0]
	v_pk_mul_f32 v[48:49], v[48:49], v[254:255] op_sel_hi:[1,0]
	v_pk_mul_f32 v[50:51], v[50:51], v[254:255] op_sel_hi:[1,0]
	v_pk_mul_f32 v[52:53], v[52:53], v[254:255] op_sel_hi:[1,0]
	v_pk_mul_f32 v[54:55], v[54:55], v[254:255] op_sel_hi:[1,0]
.Latt_nr_p0q0:
	v_mov_b32_e32 v1, v204
	v_pk_add_f32 v[72:73], v[72:73], v[204:205] op_sel_hi:[1,0] neg_lo:[0,1] neg_hi:[0,1]
	v_pk_add_f32 v[74:75], v[74:75], v[204:205] op_sel_hi:[1,0] neg_lo:[0,1] neg_hi:[0,1]
	v_pk_add_f32 v[76:77], v[76:77], v[204:205] op_sel_hi:[1,0] neg_lo:[0,1] neg_hi:[0,1]
	s_waitcnt lgkmcnt(2)
	v_mfma_f32_32x32x16_bf16 v[88:103], v[244:247], v[228:231], v[88:103]
	ds_read_b128 v[244:247], v166 offset:4096
	v_pk_add_f32 v[78:79], v[78:79], v[204:205] op_sel_hi:[1,0] neg_lo:[0,1] neg_hi:[0,1]
	v_pk_add_f32 v[80:81], v[80:81], v[204:205] op_sel_hi:[1,0] neg_lo:[0,1] neg_hi:[0,1]
	v_pk_add_f32 v[82:83], v[82:83], v[204:205] op_sel_hi:[1,0] neg_lo:[0,1] neg_hi:[0,1]
	v_pk_add_f32 v[84:85], v[84:85], v[204:205] op_sel_hi:[1,0] neg_lo:[0,1] neg_hi:[0,1]
	v_pk_add_f32 v[86:87], v[86:87], v[204:205] op_sel_hi:[1,0] neg_lo:[0,1] neg_hi:[0,1]
	v_pk_add_f32 v[104:105], v[104:105], v[204:205] op_sel_hi:[1,0] neg_lo:[0,1] neg_hi:[0,1]
	v_pk_add_f32 v[106:107], v[106:107], v[204:205] op_sel_hi:[1,0] neg_lo:[0,1] neg_hi:[0,1]
	v_pk_add_f32 v[108:109], v[108:109], v[204:205] op_sel_hi:[1,0] neg_lo:[0,1] neg_hi:[0,1]
	v_pk_add_f32 v[110:111], v[110:111], v[204:205] op_sel_hi:[1,0] neg_lo:[0,1] neg_hi:[0,1]
	v_pk_add_f32 v[112:113], v[112:113], v[204:205] op_sel_hi:[1,0] neg_lo:[0,1] neg_hi:[0,1]
	v_pk_add_f32 v[114:115], v[114:115], v[204:205] op_sel_hi:[1,0] neg_lo:[0,1] neg_hi:[0,1]
	v_pk_add_f32 v[116:117], v[116:117], v[204:205] op_sel_hi:[1,0] neg_lo:[0,1] neg_hi:[0,1]
	v_pk_add_f32 v[118:119], v[118:119], v[204:205] op_sel_hi:[1,0] neg_lo:[0,1] neg_hi:[0,1]
	s_waitcnt lgkmcnt(2)
	v_mfma_f32_32x32x16_bf16 v[120:135], v[248:251], v[228:231], v[120:135]
	ds_read_b128 v[248:251], v167 offset:0
	v_exp_f32_e32 v72, v72
	v_exp_f32_e32 v73, v73
	v_exp_f32_e32 v74, v74
	v_exp_f32_e32 v75, v75
	v_exp_f32_e32 v76, v76
	v_exp_f32_e32 v77, v77
	v_exp_f32_e32 v78, v78
	v_exp_f32_e32 v79, v79
	v_exp_f32_e32 v80, v80
	v_exp_f32_e32 v81, v81
	v_exp_f32_e32 v82, v82
	v_exp_f32_e32 v83, v83
	v_exp_f32_e32 v84, v84
	s_waitcnt lgkmcnt(2)
	v_mfma_f32_32x32x16_bf16 v[88:103], v[240:243], v[232:235], v[88:103]
	ds_read_b128 v[240:243], v167 offset:4096
	v_exp_f32_e32 v85, v85
	v_exp_f32_e32 v86, v86
	v_exp_f32_e32 v87, v87
	v_exp_f32_e32 v104, v104
	v_exp_f32_e32 v105, v105
	v_exp_f32_e32 v106, v106
	v_exp_f32_e32 v107, v107
	v_exp_f32_e32 v108, v108
	v_exp_f32_e32 v109, v109
	v_exp_f32_e32 v110, v110
	v_exp_f32_e32 v111, v111
	v_exp_f32_e32 v112, v112
	v_exp_f32_e32 v113, v113
	s_waitcnt lgkmcnt(2)
	v_mfma_f32_32x32x16_bf16 v[120:135], v[244:247], v[232:235], v[120:135]
	ds_read_b64_tr_b16 v[244:245], v199 offset:8192
	ds_read_b64_tr_b16 v[246:247], v199 offset:8704
	v_exp_f32_e32 v114, v114
	v_exp_f32_e32 v115, v115
	v_exp_f32_e32 v116, v116
	v_exp_f32_e32 v117, v117
	v_exp_f32_e32 v118, v118
	v_exp_f32_e32 v119, v119
	v_pk_add_f32 v[254:255], v[72:73], v[74:75]
	v_pk_add_f32 v[204:205], v[104:105], v[106:107]
	v_pk_add_f32 v[254:255], v[254:255], v[76:77]
	v_pk_add_f32 v[204:205], v[204:205], v[108:109]
	v_pk_add_f32 v[254:255], v[254:255], v[78:79]
	v_pk_add_f32 v[204:205], v[204:205], v[110:111]
	v_pk_add_f32 v[254:255], v[254:255], v[80:81]
	s_waitcnt lgkmcnt(3)
	v_mfma_f32_32x32x16_bf16 v[88:103], v[248:251], v[236:239], v[88:103]
	ds_read_b64_tr_b16 v[248:249], v199 offset:9216
	ds_read_b64_tr_b16 v[250:251], v199 offset:9728
	v_pk_add_f32 v[204:205], v[204:205], v[112:113]
	v_pk_add_f32 v[254:255], v[254:255], v[82:83]
	v_pk_add_f32 v[204:205], v[204:205], v[114:115]
	v_pk_add_f32 v[254:255], v[254:255], v[84:85]
	v_pk_add_f32 v[204:205], v[204:205], v[116:117]
	v_pk_add_f32 v[254:255], v[254:255], v[86:87]
	v_pk_add_f32 v[204:205], v[204:205], v[118:119]
	v_pk_add_f32 v[254:255], v[254:255], v[204:205]
	v_add_f32_e32 v254, v254, v255
	v_add_f32_e32 v3, v3, v254
	v_cvt_pk_bf16_f32 v72, v72, v73
	v_cvt_pk_bf16_f32 v73, v74, v75
	v_cvt_pk_bf16_f32 v74, v76, v77
	s_waitcnt lgkmcnt(4)
	v_mfma_f32_32x32x16_bf16 v[120:135], v[240:243], v[236:239], v[120:135]
	ds_read_b64_tr_b16 v[240:241], v199 offset:10240
	ds_read_b64_tr_b16 v[242:243], v199 offset:10752
	v_cvt_pk_bf16_f32 v75, v78, v79
	v_cvt_pk_bf16_f32 v80, v80, v81
	v_cvt_pk_bf16_f32 v81, v82, v83
	v_cvt_pk_bf16_f32 v82, v84, v85
	v_cvt_pk_bf16_f32 v83, v86, v87
	v_cvt_pk_bf16_f32 v104, v104, v105
	v_cvt_pk_bf16_f32 v105, v106, v107
	v_cvt_pk_bf16_f32 v106, v108, v109
	v_cvt_pk_bf16_f32 v107, v110, v111
	v_cvt_pk_bf16_f32 v112, v112, v113
	v_cvt_pk_bf16_f32 v113, v114, v115
	v_cvt_pk_bf16_f32 v114, v116, v117
	v_cvt_pk_bf16_f32 v115, v118, v119
	s_cmp_lt_u32 s80, 2
	s_cbranch_scc1 .Latt_mk_done_p0q1
; #define LAS __attribute__((address_space(3)))
; __device__ __forceinline__ s16x4 vtr(const LAS char* p) { return __builtin_bit_cast(s16x4, __builtin_amdgcn_ds_read_tr16_b64_v4i16((LAS v4i16_t*)p)); }
; __device__ __forceinline__ void attn_unit(LAS unsigned char* lds, const bf16* QKV, const bf16* KVC, bf16* O, const float* sink, int unit) {
;     ...
;             if (cls == 2) {
;                 const int qi = th * 64 + qg * 32 + r32;
; #pragma unroll
;                 for (int kg = 0; kg < 2; ++kg)
; #pragma unroll
;                     for (int r = 0; r < 16; ++r) { const int kj = tl * 64 + kg * 32 + crow(r, hi);
;                         const bool valid = (kj >= qi) && (kj <= qi + 256); sacc[kg][qg][r] = valid ? sacc[kg][qg][r] : -1.0e30f; }
;             }
;             float mxa = fmaxf(sacc[0][qg][0], sacc[1][qg][0]), mxb = fmaxf(sacc[0][qg][1], sacc[1][qg][1]);
; #pragma unroll
;             for (int r = 2; r < 16; r += 2) { mxa = fmaxf(fmaxf(mxa, sacc[0][qg][r]), sacc[1][qg][r]); mxb = fmaxf(fmaxf(mxb, sacc[0][qg][r + 1]), sacc[1][qg][r + 1]); }
;             float mx = fmaxf(mxa, mxb);
;             mx = fmaxf(mx, __shfl_xor(mx, 32));
;             if (__any(mx > 0.f)) {
;                 const float dl = fmaxf(mx, 0.f); mrun[qg] += dl;
;                 const float alpha = __builtin_amdgcn_exp2f(-dl); lrun[qg] *= alpha;
; #pragma unroll
;                 for (int kg = 0; kg < 2; ++kg)
; #pragma unroll
;                     for (int r = 0; r < 16; ++r) sacc[kg][qg][r] -= dl;
; #pragma unroll
;                 for (int dg = 0; dg < 2; ++dg)
; #pragma unroll
;                     for (int r = 0; r < 16; ++r) o[dg][qg][r] *= alpha;
;             }
;     ...
; #pragma unroll
;         for (int dg = 0; dg < 2; ++dg)
; #pragma unroll
;             for (int kg = 0; kg < 2; ++kg)
; #pragma unroll
;                 for (int s = 0; s < 2; ++s) {
;                     const LAS char* vp = (const LAS char*)(buf + vr_base + dg * 4096 + (kg * 32 + 16 * s) * 64);
;                     const s16x4 lo = vtr(vp), hi4 = vtr(vp + 512);
;                     const bf16x8 vf = (bf16x8){lo[0], lo[1], lo[2], lo[3], hi4[0], hi4[1], hi4[2], hi4[3]};
; #pragma unroll
;                     for (int qg = 0; qg < 2; ++qg) o[dg][qg] = __builtin_amdgcn_mfma_f32_32x32x16_bf16(vf, pf[kg][qg][s], o[dg][qg], 0, 0, 0);
	v_mov_b32_e32 v253, 0xf149f2ca
	s_cmp_eq_u32 s80, 3
	s_cbranch_scc1 .Latt_mk_up_p0q1
	v_cmp_ge_i32_e64 s[40:41], 0, v203
	v_cmp_ge_i32_e64 s[46:47], 1, v203
	v_cmp_ge_i32_e64 s[52:53], 2, v203
	v_cmp_ge_i32_e64 s[54:55], 3, v203
	v_cndmask_b32_e64 v120, v253, v120, s[40:41]
	v_cmp_ge_i32_e64 s[40:41], 8, v203
	v_cndmask_b32_e64 v121, v253, v121, s[46:47]
	v_cmp_ge_i32_e64 s[46:47], 9, v203
	v_cndmask_b32_e64 v122, v253, v122, s[52:53]
	v_cmp_ge_i32_e64 s[52:53], 10, v203
	v_cndmask_b32_e64 v123, v253, v123, s[54:55]
	v_cmp_ge_i32_e64 s[54:55], 11, v203
	v_cndmask_b32_e64 v124, v253, v124, s[40:41]
	v_cmp_ge_i32_e64 s[40:41], 16, v203
	v_cndmask_b32_e64 v125, v253, v125, s[46:47]
	v_cmp_ge_i32_e64 s[46:47], 17, v203
	v_cndmask_b32_e64 v126, v253, v126, s[52:53]
	v_cmp_ge_i32_e64 s[52:53], 18, v203
	v_cndmask_b32_e64 v127, v253, v127, s[54:55]
	v_cmp_ge_i32_e64 s[54:55], 19, v203
	v_cndmask_b32_e64 v128, v253, v128, s[40:41]
	v_cmp_ge_i32_e64 s[40:41], 24, v203
	v_cndmask_b32_e64 v129, v253, v129, s[46:47]
	v_cmp_ge_i32_e64 s[46:47], 25, v203
	v_cndmask_b32_e64 v130, v253, v130, s[52:53]
	v_cmp_ge_i32_e64 s[52:53], 26, v203
	v_cndmask_b32_e64 v131, v253, v131, s[54:55]
	v_cmp_ge_i32_e64 s[54:55], 27, v203
	v_cndmask_b32_e64 v132, v253, v132, s[40:41]
	v_cndmask_b32_e64 v133, v253, v133, s[46:47]
	v_cndmask_b32_e64 v134, v253, v134, s[52:53]
	v_cndmask_b32_e64 v135, v253, v135, s[54:55]
	v_mov_b32_e32 v88, v253
	v_mov_b32_e32 v89, v253
	v_mov_b32_e32 v90, v253
	v_mov_b32_e32 v91, v253
	v_mov_b32_e32 v92, v253
	v_mov_b32_e32 v93, v253
	v_mov_b32_e32 v94, v253
	v_mov_b32_e32 v95, v253
	v_mov_b32_e32 v96, v253
	v_mov_b32_e32 v97, v253
	v_mov_b32_e32 v98, v253
	v_mov_b32_e32 v99, v253
	v_mov_b32_e32 v100, v253
	v_mov_b32_e32 v101, v253
	v_mov_b32_e32 v102, v253
	v_mov_b32_e32 v103, v253
	s_branch .Latt_mk_done_p0q1
.Latt_mk_up_p0q1:
	v_cmp_le_i32_e64 s[40:41], 0, v203
	v_cmp_le_i32_e64 s[46:47], 1, v203
	v_cmp_le_i32_e64 s[52:53], 2, v203
	v_cmp_le_i32_e64 s[54:55], 3, v203
	v_cndmask_b32_e64 v120, v253, v120, s[40:41]
	v_cmp_le_i32_e64 s[40:41], 8, v203
	v_cndmask_b32_e64 v121, v253, v121, s[46:47]
	v_cmp_le_i32_e64 s[46:47], 9, v203
	v_cndmask_b32_e64 v122, v253, v122, s[52:53]
	v_cmp_le_i32_e64 s[52:53], 10, v203
	v_cndmask_b32_e64 v123, v253, v123, s[54:55]
	v_cmp_le_i32_e64 s[54:55], 11, v203
	v_cndmask_b32_e64 v124, v253, v124, s[40:41]
	v_cmp_le_i32_e64 s[40:41], 16, v203
	v_cndmask_b32_e64 v125, v253, v125, s[46:47]
	v_cmp_le_i32_e64 s[46:47], 17, v203
	v_cndmask_b32_e64 v126, v253, v126, s[52:53]
	v_cmp_le_i32_e64 s[52:53], 18, v203
	v_cndmask_b32_e64 v127, v253, v127, s[54:55]
	v_cmp_le_i32_e64 s[54:55], 19, v203
	v_cndmask_b32_e64 v128, v253, v128, s[40:41]
	v_cmp_le_i32_e64 s[40:41], 24, v203
	v_cndmask_b32_e64 v129, v253, v129, s[46:47]
	v_cmp_le_i32_e64 s[46:47], 25, v203
	v_cndmask_b32_e64 v130, v253, v130, s[52:53]
	v_cmp_le_i32_e64 s[52:53], 26, v203
	v_cndmask_b32_e64 v131, v253, v131, s[54:55]
	v_cmp_le_i32_e64 s[54:55], 27, v203
	v_cndmask_b32_e64 v132, v253, v132, s[40:41]
	v_cndmask_b32_e64 v133, v253, v133, s[46:47]
	v_cndmask_b32_e64 v134, v253, v134, s[52:53]
	v_cndmask_b32_e64 v135, v253, v135, s[54:55]
.Latt_mk_done_p0q1:
	s_nop 1
	s_waitcnt lgkmcnt(4)
	v_mfma_f32_32x32x16_bf16 v[8:23], v[244:247], v[72:75], v[8:23]
	ds_read_b64_tr_b16 v[244:245], v199 offset:11264
	ds_read_b64_tr_b16 v[246:247], v199 offset:11776
	v_max3_f32 v204, v88, v89, v90
	v_max3_f32 v205, v120, v121, v122
	v_max3_f32 v204, v204, v91, v92
	v_max3_f32 v205, v205, v123, v124
	v_max3_f32 v204, v204, v93, v94
	v_max3_f32 v205, v205, v125, v126
	v_max3_f32 v204, v204, v95, v96
	v_max3_f32 v205, v205, v127, v128
	v_max3_f32 v204, v204, v97, v98
	v_max3_f32 v205, v205, v129, v130
	v_max3_f32 v204, v204, v99, v100
	v_max3_f32 v205, v205, v131, v132
	s_waitcnt lgkmcnt(4)
	v_mfma_f32_32x32x16_bf16 v[8:23], v[248:251], v[80:83], v[8:23]
	ds_read_b64_tr_b16 v[248:249], v199 offset:12288
	ds_read_b64_tr_b16 v[250:251], v199 offset:12800
	v_max3_f32 v204, v204, v101, v102
	v_max3_f32 v205, v205, v133, v134
	v_max3_f32 v204, v204, v103, v135
	v_max_f32_e32 v204, v204, v205
	v_mov_b32_e32 v205, v204
	s_nop 1
	v_permlane32_swap_b32_e32 v204, v205
	v_max_f32_e32 v204, v204, v205
	v_max_f32_e32 v204, v204, v2
	v_cmp_gt_f32_e32 vcc, v204, v2
	s_cbranch_vccz .Latt_nr_p0q1
	v_sub_f32_e32 v254, v2, v204
	v_exp_f32_e32 v254, v254
	s_nop 0
	v_mul_f32_e32 v4, v4, v254
	v_pk_mul_f32 v[24:25], v[24:25], v[254:255] op_sel_hi:[1,0]
	v_pk_mul_f32 v[26:27], v[26:27], v[254:255] op_sel_hi:[1,0]
	v_pk_mul_f32 v[28:29], v[28:29], v[254:255] op_sel_hi:[1,0]
	v_pk_mul_f32 v[30:31], v[30:31], v[254:255] op_sel_hi:[1,0]
	v_pk_mul_f32 v[32:33], v[32:33], v[254:255] op_sel_hi:[1,0]
	v_pk_mul_f32 v[34:35], v[34:35], v[254:255] op_sel_hi:[1,0]
	v_pk_mul_f32 v[36:37], v[36:37], v[254:255] op_sel_hi:[1,0]
	v_pk_mul_f32 v[38:39], v[38:39], v[254:255] op_sel_hi:[1,0]
	v_pk_mul_f32 v[56:57], v[56:57], v[254:255] op_sel_hi:[1,0]
	v_pk_mul_f32 v[58:59], v[58:59], v[254:255] op_sel_hi:[1,0]
	v_pk_mul_f32 v[60:61], v[60:61], v[254:255] op_sel_hi:[1,0]
	v_pk_mul_f32 v[62:63], v[62:63], v[254:255] op_sel_hi:[1,0]
	v_pk_mul_f32 v[64:65], v[64:65], v[254:255] op_sel_hi:[1,0]
	v_pk_mul_f32 v[66:67], v[66:67], v[254:255] op_sel_hi:[1,0]
	v_pk_mul_f32 v[68:69], v[68:69], v[254:255] op_sel_hi:[1,0]
	v_pk_mul_f32 v[70:71], v[70:71], v[254:255] op_sel_hi:[1,0]
; __device__ __forceinline__ unsigned cvt_pk_bf16(float lo, float hi) { f32x2_t v = {lo, hi}; bf16x2_t b = __builtin_convertvector(v, bf16x2_t); return __builtin_bit_cast(unsigned, b); }
; #define LAS __attribute__((address_space(3)))
; __device__ __forceinline__ s16x4 vtr(const LAS char* p) { return __builtin_bit_cast(s16x4, __builtin_amdgcn_ds_read_tr16_b64_v4i16((LAS v4i16_t*)p)); }
; __device__ __forceinline__ void attn_unit(LAS unsigned char* lds, const bf16* QKV, const bf16* KVC, bf16* O, const float* sink, int unit) {
;     ...
;             float psa = 0.f, psb = 0.f;
; #pragma unroll
;             for (int kg = 0; kg < 2; ++kg)
; #pragma unroll
;                 for (int r = 0; r < 16; r += 2) { const float p0 = __builtin_amdgcn_exp2f(sacc[kg][qg][r]), p1 = __builtin_amdgcn_exp2f(sacc[kg][qg][r + 1]); sacc[kg][qg][r] = p0; sacc[kg][qg][r + 1] = p1; psa += p0; psb += p1; }
;             lrun[qg] += psa + psb;
; #pragma unroll
;             for (int kg = 0; kg < 2; ++kg)
; #pragma unroll
;                 for (int s = 0; s < 2; ++s) { u32x4 w;
;                     w.x = cvt_pk_bf16(sacc[kg][qg][8 * s + 0], sacc[kg][qg][8 * s + 1]); w.y = cvt_pk_bf16(sacc[kg][qg][8 * s + 2], sacc[kg][qg][8 * s + 3]);
;                     w.z = cvt_pk_bf16(sacc[kg][qg][8 * s + 4], sacc[kg][qg][8 * s + 5]); w.w = cvt_pk_bf16(sacc[kg][qg][8 * s + 6], sacc[kg][qg][8 * s + 7]);
;                     pf[kg][qg][s] = __builtin_bit_cast(bf16x8, w); }
;         }
; #pragma unroll
;         for (int dg = 0; dg < 2; ++dg)
; #pragma unroll
;             for (int kg = 0; kg < 2; ++kg)
; #pragma unroll
;                 for (int s = 0; s < 2; ++s) {
;                     const LAS char* vp = (const LAS char*)(buf + vr_base + dg * 4096 + (kg * 32 + 16 * s) * 64);
;                     const s16x4 lo = vtr(vp), hi4 = vtr(vp + 512);
;                     const bf16x8 vf = (bf16x8){lo[0], lo[1], lo[2], lo[3], hi4[0], hi4[1], hi4[2], hi4[3]};
; #pragma unroll
;                     for (int qg = 0; qg < 2; ++qg) o[dg][qg] = __builtin_amdgcn_mfma_f32_32x32x16_bf16(vf, pf[kg][qg][s], o[dg][qg], 0, 0, 0);
;                 }
.Latt_nr_p0q1:
	v_mov_b32_e32 v2, v204
	v_pk_add_f32 v[88:89], v[88:89], v[204:205] op_sel_hi:[1,0] neg_lo:[0,1] neg_hi:[0,1]
	v_pk_add_f32 v[90:91], v[90:91], v[204:205] op_sel_hi:[1,0] neg_lo:[0,1] neg_hi:[0,1]
	v_pk_add_f32 v[92:93], v[92:93], v[204:205] op_sel_hi:[1,0] neg_lo:[0,1] neg_hi:[0,1]
	s_waitcnt lgkmcnt(4)
	v_mfma_f32_32x32x16_bf16 v[8:23], v[240:243], v[104:107], v[8:23]
	ds_read_b64_tr_b16 v[240:241], v199 offset:13312
	ds_read_b64_tr_b16 v[242:243], v199 offset:13824
	v_pk_add_f32 v[94:95], v[94:95], v[204:205] op_sel_hi:[1,0] neg_lo:[0,1] neg_hi:[0,1]
	v_pk_add_f32 v[96:97], v[96:97], v[204:205] op_sel_hi:[1,0] neg_lo:[0,1] neg_hi:[0,1]
	v_pk_add_f32 v[98:99], v[98:99], v[204:205] op_sel_hi:[1,0] neg_lo:[0,1] neg_hi:[0,1]
	v_pk_add_f32 v[100:101], v[100:101], v[204:205] op_sel_hi:[1,0] neg_lo:[0,1] neg_hi:[0,1]
	v_pk_add_f32 v[102:103], v[102:103], v[204:205] op_sel_hi:[1,0] neg_lo:[0,1] neg_hi:[0,1]
	v_pk_add_f32 v[120:121], v[120:121], v[204:205] op_sel_hi:[1,0] neg_lo:[0,1] neg_hi:[0,1]
	v_pk_add_f32 v[122:123], v[122:123], v[204:205] op_sel_hi:[1,0] neg_lo:[0,1] neg_hi:[0,1]
	v_pk_add_f32 v[124:125], v[124:125], v[204:205] op_sel_hi:[1,0] neg_lo:[0,1] neg_hi:[0,1]
	v_pk_add_f32 v[126:127], v[126:127], v[204:205] op_sel_hi:[1,0] neg_lo:[0,1] neg_hi:[0,1]
	v_pk_add_f32 v[128:129], v[128:129], v[204:205] op_sel_hi:[1,0] neg_lo:[0,1] neg_hi:[0,1]
	v_pk_add_f32 v[130:131], v[130:131], v[204:205] op_sel_hi:[1,0] neg_lo:[0,1] neg_hi:[0,1]
	v_pk_add_f32 v[132:133], v[132:133], v[204:205] op_sel_hi:[1,0] neg_lo:[0,1] neg_hi:[0,1]
	v_pk_add_f32 v[134:135], v[134:135], v[204:205] op_sel_hi:[1,0] neg_lo:[0,1] neg_hi:[0,1]
	s_waitcnt lgkmcnt(4)
	v_mfma_f32_32x32x16_bf16 v[8:23], v[244:247], v[112:115], v[8:23]
	ds_read_b64_tr_b16 v[244:245], v199 offset:14336
	ds_read_b64_tr_b16 v[246:247], v199 offset:14848
	v_exp_f32_e32 v88, v88
	v_exp_f32_e32 v89, v89
	v_exp_f32_e32 v90, v90
	v_exp_f32_e32 v91, v91
	v_exp_f32_e32 v92, v92
	v_exp_f32_e32 v93, v93
	v_exp_f32_e32 v94, v94
	v_exp_f32_e32 v95, v95
	v_exp_f32_e32 v96, v96
	v_exp_f32_e32 v97, v97
	v_exp_f32_e32 v98, v98
	v_exp_f32_e32 v99, v99
	v_exp_f32_e32 v100, v100
	s_waitcnt lgkmcnt(4)
	v_mfma_f32_32x32x16_bf16 v[40:55], v[248:251], v[72:75], v[40:55]
	ds_read_b64_tr_b16 v[248:249], v199 offset:15360
	ds_read_b64_tr_b16 v[250:251], v199 offset:15872
	v_exp_f32_e32 v101, v101
	v_exp_f32_e32 v102, v102
	v_exp_f32_e32 v103, v103
	v_exp_f32_e32 v120, v120
	v_exp_f32_e32 v121, v121
	v_exp_f32_e32 v122, v122
	v_exp_f32_e32 v123, v123
	v_exp_f32_e32 v124, v124
	v_exp_f32_e32 v125, v125
	v_exp_f32_e32 v126, v126
	v_exp_f32_e32 v127, v127
	v_exp_f32_e32 v128, v128
	v_exp_f32_e32 v129, v129
	s_waitcnt lgkmcnt(4)
	v_mfma_f32_32x32x16_bf16 v[40:55], v[240:243], v[80:83], v[40:55]
	ds_read_b64_tr_b16 v[240:241], v199 offset:8192
	ds_read_b64_tr_b16 v[242:243], v199 offset:8704
	v_exp_f32_e32 v130, v130
	v_exp_f32_e32 v131, v131
	v_exp_f32_e32 v132, v132
	v_exp_f32_e32 v133, v133
	v_exp_f32_e32 v134, v134
	v_exp_f32_e32 v135, v135
	v_pk_add_f32 v[254:255], v[88:89], v[90:91]
	v_pk_add_f32 v[204:205], v[120:121], v[122:123]
	v_pk_add_f32 v[254:255], v[254:255], v[92:93]
	v_pk_add_f32 v[204:205], v[204:205], v[124:125]
	v_pk_add_f32 v[254:255], v[254:255], v[94:95]
	v_pk_add_f32 v[204:205], v[204:205], v[126:127]
	v_pk_add_f32 v[254:255], v[254:255], v[96:97]
	s_waitcnt lgkmcnt(4)
	v_mfma_f32_32x32x16_bf16 v[40:55], v[244:247], v[104:107], v[40:55]
	ds_read_b64_tr_b16 v[244:245], v199 offset:9216
	ds_read_b64_tr_b16 v[246:247], v199 offset:9728
	v_pk_add_f32 v[204:205], v[204:205], v[128:129]
	v_pk_add_f32 v[254:255], v[254:255], v[98:99]
	v_pk_add_f32 v[204:205], v[204:205], v[130:131]
	v_pk_add_f32 v[254:255], v[254:255], v[100:101]
	v_pk_add_f32 v[204:205], v[204:205], v[132:133]
	v_pk_add_f32 v[254:255], v[254:255], v[102:103]
	v_pk_add_f32 v[204:205], v[204:205], v[134:135]
	v_pk_add_f32 v[254:255], v[254:255], v[204:205]
	v_add_f32_e32 v254, v254, v255
	v_add_f32_e32 v4, v4, v254
	v_cvt_pk_bf16_f32 v88, v88, v89
	v_cvt_pk_bf16_f32 v89, v90, v91
	v_cvt_pk_bf16_f32 v90, v92, v93
	s_waitcnt lgkmcnt(4)
	v_mfma_f32_32x32x16_bf16 v[40:55], v[248:251], v[112:115], v[40:55]
	ds_read_b64_tr_b16 v[248:249], v199 offset:10240
	ds_read_b64_tr_b16 v[250:251], v199 offset:10752
	v_cvt_pk_bf16_f32 v91, v94, v95
	v_cvt_pk_bf16_f32 v96, v96, v97
	v_cvt_pk_bf16_f32 v97, v98, v99
	v_cvt_pk_bf16_f32 v98, v100, v101
	v_cvt_pk_bf16_f32 v99, v102, v103
	v_cvt_pk_bf16_f32 v120, v120, v121
	v_cvt_pk_bf16_f32 v121, v122, v123
	v_cvt_pk_bf16_f32 v122, v124, v125
	v_cvt_pk_bf16_f32 v123, v126, v127
	v_cvt_pk_bf16_f32 v128, v128, v129
	v_cvt_pk_bf16_f32 v129, v130, v131
	v_cvt_pk_bf16_f32 v130, v132, v133
	v_cvt_pk_bf16_f32 v131, v134, v135
	s_nop 1
	s_waitcnt lgkmcnt(4)
	v_mfma_f32_32x32x16_bf16 v[24:39], v[240:243], v[88:91], v[24:39]
	ds_read_b64_tr_b16 v[240:241], v199 offset:11264
	ds_read_b64_tr_b16 v[242:243], v199 offset:11776
	s_waitcnt lgkmcnt(4)
	v_mfma_f32_32x32x16_bf16 v[24:39], v[244:247], v[96:99], v[24:39]
	ds_read_b64_tr_b16 v[244:245], v199 offset:12288
	ds_read_b64_tr_b16 v[246:247], v199 offset:12800
	s_waitcnt lgkmcnt(4)
	v_mfma_f32_32x32x16_bf16 v[24:39], v[248:251], v[120:123], v[24:39]
	ds_read_b64_tr_b16 v[248:249], v199 offset:13312
	ds_read_b64_tr_b16 v[250:251], v199 offset:13824
	s_waitcnt lgkmcnt(4)
	v_mfma_f32_32x32x16_bf16 v[24:39], v[240:243], v[128:131], v[24:39]
	ds_read_b64_tr_b16 v[240:241], v199 offset:14336
	ds_read_b64_tr_b16 v[242:243], v199 offset:14848
	s_waitcnt lgkmcnt(4)
	v_mfma_f32_32x32x16_bf16 v[56:71], v[244:247], v[88:91], v[56:71]
	ds_read_b64_tr_b16 v[244:245], v199 offset:15360
	ds_read_b64_tr_b16 v[246:247], v199 offset:15872
	s_waitcnt lgkmcnt(4)
	v_mfma_f32_32x32x16_bf16 v[56:71], v[248:251], v[96:99], v[56:71]
	s_waitcnt lgkmcnt(2)
	v_mfma_f32_32x32x16_bf16 v[56:71], v[240:243], v[120:123], v[56:71]
	s_waitcnt lgkmcnt(0)
	v_mfma_f32_32x32x16_bf16 v[56:71], v[244:247], v[128:131], v[56:71]
; __device__ __forceinline__ unsigned cvt_pk_bf16(float lo, float hi) { f32x2_t v = {lo, hi}; bf16x2_t b = __builtin_convertvector(v, bf16x2_t); return __builtin_bit_cast(unsigned, b); }
; #define LAS __attribute__((address_space(3)))
; __device__ __forceinline__ void attn_unit(LAS unsigned char* lds, const bf16* QKV, const bf16* KVC, bf16* O, const float* sink, int unit) {
;     ...
;     for (int qg = 0; qg < 2; ++qg)
; #pragma unroll
;         for (int ks = 0; ks < 4; ++ks) qf[qg][ks] = *(const bf16x8*)(QKV + (t0 + th * 64 + qg * 32 + r32) * NIN0 + h * 64 + ks * 16 + hi * 8);
;     LAS unsigned char* qlds = lds + 32768 + wid * 8192 + lane * 16;
; #pragma unroll
;     for (int qg = 0; qg < 2; ++qg)
; #pragma unroll
;         for (int ks = 0; ks < 4; ++ks) *(LAS bf16x8*)(qlds + (qg * 4 + ks) * 1024) = qf[qg][ks];
;     float mrun[2], lrun[2]; f32x16 o[2][2];
;     const float sk = sink[h] * LOG2E;
;     ...
; #pragma unroll
;     for (int qg = 0; qg < 2; ++qg) {
;         const float lt = lrun[qg] + __shfl_xor(lrun[qg], 32); const float inv = 1.0f / lt;
;         bf16* op = O + (t0 + th * 64 + qg * 32 + r32) * D + h * 64 + 4 * hi;
; #pragma unroll
;         for (int dg = 0; dg < 2; ++dg)
; #pragma unroll
;             for (int rg = 0; rg < 4; ++rg) { u32x2 w; w.x = cvt_pk_bf16(o[dg][qg][4 * rg] * inv, o[dg][qg][4 * rg + 1] * inv); w.y = cvt_pk_bf16(o[dg][qg][4 * rg + 2] * inv, o[dg][qg][4 * rg + 3] * inv);
;                 *(u32x2*)(op + dg * 32 + 8 * rg) = w; }
;     }
.Latt_skip:
	s_add_u32 s77, s77, 1
	s_cmp_lt_u32 s77, 10
	s_cbranch_scc1 .Latt_tile
	s_nop 11
	s_cmp_eq_u32 s76, 0
	s_cbranch_scc0 .Latt_noq
	s_mov_b32 s91, 1
	v_readlane_b32 s40, v252, 13
	v_readlane_b32 s41, v252, 14
	s_lshl_b32 s4, s8, 7
	s_lshl_b32 s5, s74, 6
	s_add_u32 s4, s4, s5
	s_lshl_b32 s12, s91, 2
	s_add_u32 s12, s12, s75
	s_lshl_b32 s88, s12, 7
	s_mul_i32 s5, s4, 0xe00
	s_add_u32 s5, s5, s88
	s_add_u32 s52, s48, s5
	s_addc_u32 s53, s49, 0
	v_and_b32_e32 v205, 31, v206
	v_bfe_u32 v207, v206, 5, 1
	v_mul_u32_u24_e32 v204, 0xe00, v205
	v_lshl_add_u32 v204, v207, 4, v204
	v_add_u32_e32 v253, 0x1c000, v204
	global_load_dwordx4 v[208:211], v204, s[52:53] offset:0
	global_load_dwordx4 v[212:215], v204, s[52:53] offset:32
	global_load_dwordx4 v[216:219], v204, s[52:53] offset:64
	global_load_dwordx4 v[220:223], v204, s[52:53] offset:96
	global_load_dwordx4 v[224:227], v253, s[52:53] offset:0
	global_load_dwordx4 v[228:231], v253, s[52:53] offset:32
	global_load_dwordx4 v[232:235], v253, s[52:53] offset:64
	global_load_dwordx4 v[236:239], v253, s[52:53] offset:96
	s_lshl_b32 s12, s12, 2
	s_load_dword s47, s[40:41], s12
.Latt_noq:
	v_and_b32_e32 v205, 31, v206
	v_bfe_u32 v207, v206, 5, 1
	v_lshlrev_b32_e32 v253, 11, v205
	v_lshl_add_u32 v253, v207, 3, v253
	v_mov_b32_e32 v204, v3
	v_mov_b32_e32 v205, v3
	s_nop 1
	v_permlane32_swap_b32_e32 v204, v205
	v_add_f32_e32 v204, v204, v205
	v_rcp_f32_e32 v254, v204
	s_nop 0
	v_fma_f32 v205, -v204, v254, 1.0
	v_fmac_f32_e32 v254, v205, v254
	v_pk_mul_f32 v[8:9], v[8:9], v[254:255] op_sel_hi:[1,0]
	v_pk_mul_f32 v[10:11], v[10:11], v[254:255] op_sel_hi:[1,0]
	v_pk_mul_f32 v[12:13], v[12:13], v[254:255] op_sel_hi:[1,0]
	v_pk_mul_f32 v[14:15], v[14:15], v[254:255] op_sel_hi:[1,0]
	v_pk_mul_f32 v[16:17], v[16:17], v[254:255] op_sel_hi:[1,0]
	v_pk_mul_f32 v[18:19], v[18:19], v[254:255] op_sel_hi:[1,0]
	v_pk_mul_f32 v[20:21], v[20:21], v[254:255] op_sel_hi:[1,0]
	v_pk_mul_f32 v[22:23], v[22:23], v[254:255] op_sel_hi:[1,0]
	v_cvt_pk_bf16_f32 v8, v8, v9
	v_cvt_pk_bf16_f32 v9, v10, v11
	v_cvt_pk_bf16_f32 v12, v12, v13
	v_cvt_pk_bf16_f32 v13, v14, v15
	v_cvt_pk_bf16_f32 v16, v16, v17
	v_cvt_pk_bf16_f32 v17, v18, v19
	v_cvt_pk_bf16_f32 v20, v20, v21
	v_cvt_pk_bf16_f32 v21, v22, v23
	global_store_dwordx2 v253, v[8:9], s[98:99] offset:0
	global_store_dwordx2 v253, v[12:13], s[98:99] offset:16
	global_store_dwordx2 v253, v[16:17], s[98:99] offset:32
	global_store_dwordx2 v253, v[20:21], s[98:99] offset:48
	v_pk_mul_f32 v[40:41], v[40:41], v[254:255] op_sel_hi:[1,0]
	v_pk_mul_f32 v[42:43], v[42:43], v[254:255] op_sel_hi:[1,0]
	v_pk_mul_f32 v[44:45], v[44:45], v[254:255] op_sel_hi:[1,0]
	v_pk_mul_f32 v[46:47], v[46:47], v[254:255] op_sel_hi:[1,0]
	v_pk_mul_f32 v[48:49], v[48:49], v[254:255] op_sel_hi:[1,0]
	v_pk_mul_f32 v[50:51], v[50:51], v[254:255] op_sel_hi:[1,0]
	v_pk_mul_f32 v[52:53], v[52:53], v[254:255] op_sel_hi:[1,0]
	v_pk_mul_f32 v[54:55], v[54:55], v[254:255] op_sel_hi:[1,0]
	v_cvt_pk_bf16_f32 v40, v40, v41
	v_cvt_pk_bf16_f32 v41, v42, v43
	v_cvt_pk_bf16_f32 v44, v44, v45
	v_cvt_pk_bf16_f32 v45, v46, v47
	v_cvt_pk_bf16_f32 v48, v48, v49
	v_cvt_pk_bf16_f32 v49, v50, v51
	v_cvt_pk_bf16_f32 v52, v52, v53
	v_cvt_pk_bf16_f32 v53, v54, v55
	global_store_dwordx2 v253, v[40:41], s[98:99] offset:64
	global_store_dwordx2 v253, v[44:45], s[98:99] offset:80
	global_store_dwordx2 v253, v[48:49], s[98:99] offset:96
	global_store_dwordx2 v253, v[52:53], s[98:99] offset:112
	v_mov_b32_e32 v204, v4
	v_mov_b32_e32 v205, v4
	s_nop 1
	v_permlane32_swap_b32_e32 v204, v205
	v_add_f32_e32 v204, v204, v205
	v_rcp_f32_e32 v254, v204
	s_nop 0
	v_fma_f32 v205, -v204, v254, 1.0
	v_fmac_f32_e32 v254, v205, v254
	v_add_u32_e32 v253, 0x10000, v253
	v_pk_mul_f32 v[24:25], v[24:25], v[254:255] op_sel_hi:[1,0]
	v_pk_mul_f32 v[26:27], v[26:27], v[254:255] op_sel_hi:[1,0]
	v_pk_mul_f32 v[28:29], v[28:29], v[254:255] op_sel_hi:[1,0]
	v_pk_mul_f32 v[30:31], v[30:31], v[254:255] op_sel_hi:[1,0]
	v_pk_mul_f32 v[32:33], v[32:33], v[254:255] op_sel_hi:[1,0]
	v_pk_mul_f32 v[34:35], v[34:35], v[254:255] op_sel_hi:[1,0]
	v_pk_mul_f32 v[36:37], v[36:37], v[254:255] op_sel_hi:[1,0]
	v_pk_mul_f32 v[38:39], v[38:39], v[254:255] op_sel_hi:[1,0]
	v_cvt_pk_bf16_f32 v24, v24, v25
	v_cvt_pk_bf16_f32 v25, v26, v27
	v_cvt_pk_bf16_f32 v28, v28, v29
	v_cvt_pk_bf16_f32 v29, v30, v31
	v_cvt_pk_bf16_f32 v32, v32, v33
	v_cvt_pk_bf16_f32 v33, v34, v35
	v_cvt_pk_bf16_f32 v36, v36, v37
	v_cvt_pk_bf16_f32 v37, v38, v39
	global_store_dwordx2 v253, v[24:25], s[98:99] offset:0
	global_store_dwordx2 v253, v[28:29], s[98:99] offset:16
	global_store_dwordx2 v253, v[32:33], s[98:99] offset:32
	global_store_dwordx2 v253, v[36:37], s[98:99] offset:48
	v_pk_mul_f32 v[56:57], v[56:57], v[254:255] op_sel_hi:[1,0]
	v_pk_mul_f32 v[58:59], v[58:59], v[254:255] op_sel_hi:[1,0]
	v_pk_mul_f32 v[60:61], v[60:61], v[254:255] op_sel_hi:[1,0]
	v_pk_mul_f32 v[62:63], v[62:63], v[254:255] op_sel_hi:[1,0]
	v_pk_mul_f32 v[64:65], v[64:65], v[254:255] op_sel_hi:[1,0]
	v_pk_mul_f32 v[66:67], v[66:67], v[254:255] op_sel_hi:[1,0]
	v_pk_mul_f32 v[68:69], v[68:69], v[254:255] op_sel_hi:[1,0]
	v_pk_mul_f32 v[70:71], v[70:71], v[254:255] op_sel_hi:[1,0]
	v_cvt_pk_bf16_f32 v56, v56, v57
	v_cvt_pk_bf16_f32 v57, v58, v59
	v_cvt_pk_bf16_f32 v60, v60, v61
	v_cvt_pk_bf16_f32 v61, v62, v63
	v_cvt_pk_bf16_f32 v64, v64, v65
	v_cvt_pk_bf16_f32 v65, v66, v67
	v_cvt_pk_bf16_f32 v68, v68, v69
	v_cvt_pk_bf16_f32 v69, v70, v71
	global_store_dwordx2 v253, v[56:57], s[98:99] offset:64
	global_store_dwordx2 v253, v[60:61], s[98:99] offset:80
	global_store_dwordx2 v253, v[64:65], s[98:99] offset:96
	global_store_dwordx2 v253, v[68:69], s[98:99] offset:112
	s_add_u32 s76, s76, 1
	s_cmp_lt_u32 s76, 2
	s_cbranch_scc0 .Latt_done
	s_waitcnt vmcnt(16)
	s_branch .Latt_unit
.Latt_done:
	s_waitcnt vmcnt(0)
	v_readfirstlane_b32 s12, v206
	s_mov_b64 s[42:43], 0
	s_nop 1
	s_and_b32 s4, s12, 0xffffffc0
	s_ashr_i32 s5, s4, 31
	v_lshl_add_u64 v[6:7], s[4:5], 2, v[144:145]
	s_branch .Latt_join

; #define LAS __attribute__((address_space(3)))
; __device__ __forceinline__ void gate_unit(LAS unsigned char* lds, const bf16* QKV, bf16* O, const float* vnorm, const bf16* wsg, const float* bsg, int unit) {
;     const int tid = threadIdx.x, lane = tid & 63, wid = __builtin_amdgcn_readfirstlane(tid >> 6), r32 = lane & 31, hi = lane >> 5;
;     const int g = wid; const size_t t0 = (size_t)unit * 128;
;     LAS unsigned char* img = lds + wid * 16384;
;     {
;         const int d8 = lane & 7;
;         const f32x4 n0 = *(const f32x4*)(vnorm + g * 64 + d8 * 8), n1 = *(const f32x4*)(vnorm + g * 64 + d8 * 8 + 4);
; #pragma unroll 8
;         for (int it = 0; it < 16; ++it) {
;             const int j = it * 8 + (lane >> 3);
;             const u32x4 w = *(const u32x4*)(QKV + (t0 + j) * NIN0 + 1280 + g * 64 + d8 * 8);
.Latt_join:
	s_barrier
	global_load_dwordx4 v[2:5], v[6:7], off
	s_nop 0
	global_load_dwordx4 v[6:9], v[6:7], off offset:16
	s_lshr_b32 s12, s12, 6
	s_lshl_b32 s46, s12, 14
	s_lshl_b64 s[40:41], s[4:5], 1
	v_add_u32_e32 v1, s46, v191
	v_lshl_add_u64 v[10:11], v[152:153], 0, s[40:41]
